# GLA scan: the slot-switch MFMAs accumulate in place in v[16:31]; the 16 v_mov_b64 accumulator copies per block are gone
# baseline (speedup 1.0000x reference)
.LBB0_704:
	s_ashr_i32 s81, s80, 4
	s_and_b32 s82, s80, 15
	s_mul_i32 s6, s81, 0x10800
	s_mul_hi_i32 s7, s81, 0x10800
	s_add_u32 s4, s6, s28
	s_addc_u32 s5, s7, 0
	s_lshl_b64 s[4:5], s[4:5], 4
	s_add_u32 s6, s6, s30
	s_addc_u32 s7, s7, 0
	s_lshl_b64 s[6:7], s[6:7], 4
	s_add_u32 s6, s63, s6
	s_addc_u32 s7, s64, s7
	s_mul_i32 s8, s81, 0x4200
	s_mul_hi_i32 s9, s81, 0x4200
	s_add_u32 s8, s8, s34
	s_addc_u32 s9, s9, s35
	s_mul_i32 s10, s81, 0x21000
	s_lshl_b32 s12, s82, 8
	s_mul_hi_i32 s11, s81, 0x21000
	s_or_b32 s10, s10, s12
	s_lshl_b64 s[8:9], s[8:9], 4
	s_lshl_b64 s[10:11], s[10:11], 4
	s_add_u32 s12, s66, s10
	s_addc_u32 s13, s67, s11
	s_mul_i32 s10, s81, 0x2100
	s_mul_hi_i32 s11, s81, 0x2100
	s_add_u32 s10, s10, s36
	s_addc_u32 s11, s11, 0
	s_lshl_b64 s[10:11], s[10:11], 2
	s_add_u32 s4, s33, s4
	s_addc_u32 s5, s62, s5
	s_add_u32 s8, s68, s8
	s_addc_u32 s9, s69, s9
	s_add_u32 s10, s70, s10
	s_addc_u32 s11, s71, s11
	v_lshl_add_u64 v[124:125], s[6:7], 0, v[138:139]
	v_lshl_add_u64 v[126:127], s[10:11], 0, v[142:143]
	s_barrier
	global_load_dwordx4 v[16:19], v[124:125], off
	global_load_dwordx4 v[20:23], v[124:125], off offset:1024
	global_load_dwordx4 v[24:27], v[124:125], off offset:2048
	global_load_dwordx4 v[28:31], v[124:125], off offset:3072
	global_load_dwordx4 v[0:3], v[126:127], off
	global_load_dwordx4 v[4:7], v[126:127], off offset:32
	global_load_dwordx4 v[8:11], v[126:127], off offset:64
	global_load_dwordx4 v[12:15], v[126:127], off offset:96
	v_lshl_add_u64 v[132:133], s[12:13], 0, v[138:139]
	global_load_dwordx4 v[32:35], v[132:133], off
	global_load_dwordx4 v[36:39], v[132:133], off offset:1024
	global_load_dwordx4 v[40:43], v[132:133], off offset:2048
	global_load_dwordx4 v[44:47], v[132:133], off offset:3072
	v_lshl_add_u64 v[128:129], s[4:5], 0, v[138:139]
	s_mov_b32 s4, 0xc000
	v_add_co_u32_e32 v50, vcc, s4, v128
	v_lshl_add_u64 v[130:131], s[8:9], 0, v[138:139]
	s_nop 0
	v_addc_co_u32_e32 v51, vcc, 0, v129, vcc
	s_movk_i32 s4, 0x2000
	global_load_dwordx4 v[100:103], v[50:51], off
	global_load_dwordx4 v[104:107], v[50:51], off offset:1024
	v_add_co_u32_e32 v50, vcc, s4, v130
	s_waitcnt vmcnt(9)
	v_pk_mul_f32 v[2:3], v[2:3], 0 op_sel_hi:[1,0]
	v_addc_co_u32_e32 v51, vcc, 0, v131, vcc
	s_waitcnt vmcnt(6)
	v_pk_mul_f32 v[14:15], v[14:15], 0 op_sel_hi:[1,0]
	v_pk_mul_f32 v[10:11], v[10:11], 0 op_sel_hi:[1,0]
	v_pk_mul_f32 v[6:7], v[6:7], 0 op_sel_hi:[1,0]
	v_pk_mul_f32 v[12:13], v[12:13], 0 op_sel_hi:[1,0]
	v_pk_mul_f32 v[8:9], v[8:9], 0 op_sel_hi:[1,0]
	v_pk_mul_f32 v[4:5], v[4:5], 0 op_sel_hi:[1,0]
	v_pk_mul_f32 v[0:1], v[0:1], 0 op_sel_hi:[1,0]
	global_load_dwordx4 v[54:57], v[50:51], off
	s_waitcnt vmcnt(6)
	v_mfma_f32_32x32x16_bf16 v[0:15], v[16:19], v[32:35], v[0:15]
	v_add_co_u32_e32 v16, vcc, s29, v124
	s_nop 1
	v_addc_co_u32_e32 v17, vcc, 0, v125, vcc
	global_load_dwordx4 v[68:71], v[16:17], off
	global_load_dwordx4 v[50:53], v[16:17], off offset:1024
	global_load_dwordx4 v[60:63], v[16:17], off offset:2048
	global_load_dwordx4 v[64:67], v[16:17], off offset:3072
	global_load_dwordx4 v[92:95], v[126:127], off offset:1024
	global_load_dwordx4 v[84:87], v[126:127], off offset:1056
	global_load_dwordx4 v[88:91], v[126:127], off offset:1088
	global_load_dwordx4 v[96:99], v[126:127], off offset:1120
	v_add_co_u32_e32 v16, vcc, s74, v132
	s_waitcnt vmcnt(13)
	v_mfma_f32_32x32x16_bf16 v[0:15], v[20:23], v[36:39], v[0:15]
	v_addc_co_u32_e32 v17, vcc, 0, v133, vcc
	global_load_dwordx4 v[108:111], v[16:17], off
	global_load_dwordx4 v[72:75], v[16:17], off offset:1024
	global_load_dwordx4 v[76:79], v[16:17], off offset:2048
	global_load_dwordx4 v[80:83], v[16:17], off offset:3072
	v_add_co_u32_e32 v16, vcc, s29, v128
	s_nop 1
	v_addc_co_u32_e32 v17, vcc, 0, v129, vcc
	global_load_dwordx4 v[32:35], v[16:17], off offset:1024
	s_nop 0
	global_load_dwordx4 v[16:19], v[16:17], off
	s_waitcnt vmcnt(18)
	v_mfma_f32_32x32x16_bf16 v[0:15], v[24:27], v[40:43], v[0:15]
	s_andn2_b64 vcc, exec, s[38:39]
	s_waitcnt vmcnt(17)
	v_mfma_f32_32x32x16_bf16 v[0:15], v[28:31], v[44:47], v[0:15]
	s_nop 11
	v_and_b32_sdwa v22, v3, v238 dst_sel:DWORD dst_unused:UNUSED_PAD src0_sel:WORD_1 src1_sel:DWORD
	v_and_b32_sdwa v23, v1, v238 dst_sel:DWORD dst_unused:UNUSED_PAD src0_sel:WORD_1 src1_sel:DWORD
	v_and_b32_sdwa v20, v2, v238 dst_sel:DWORD dst_unused:UNUSED_PAD src0_sel:WORD_1 src1_sel:DWORD
	v_and_b32_sdwa v21, v0, v238 dst_sel:DWORD dst_unused:UNUSED_PAD src0_sel:WORD_1 src1_sel:DWORD
	v_add3_u32 v22, v3, v22, s31
	v_add3_u32 v23, v1, v23, s31
	v_add3_u32 v21, v0, v21, s31
	v_add3_u32 v20, v2, v20, s31
	v_and_b32_e32 v22, 0xffff0000, v22
	v_and_b32_e32 v23, 0xffff0000, v23
	v_or_b32_sdwa v113, v22, v20 dst_sel:DWORD dst_unused:UNUSED_PAD src0_sel:DWORD src1_sel:WORD_1
	v_or_b32_sdwa v112, v23, v21 dst_sel:DWORD dst_unused:UNUSED_PAD src0_sel:DWORD src1_sel:WORD_1
	v_and_b32_sdwa v22, v7, v238 dst_sel:DWORD dst_unused:UNUSED_PAD src0_sel:WORD_1 src1_sel:DWORD
	v_and_b32_sdwa v23, v5, v238 dst_sel:DWORD dst_unused:UNUSED_PAD src0_sel:WORD_1 src1_sel:DWORD
	v_and_b32_sdwa v20, v6, v238 dst_sel:DWORD dst_unused:UNUSED_PAD src0_sel:WORD_1 src1_sel:DWORD
	v_and_b32_sdwa v21, v4, v238 dst_sel:DWORD dst_unused:UNUSED_PAD src0_sel:WORD_1 src1_sel:DWORD
	v_add3_u32 v22, v7, v22, s31
	v_add3_u32 v23, v5, v23, s31
	v_add3_u32 v21, v4, v21, s31
	v_add3_u32 v20, v6, v20, s31
	v_and_b32_e32 v22, 0xffff0000, v22
	v_and_b32_e32 v23, 0xffff0000, v23
	v_or_b32_sdwa v115, v22, v20 dst_sel:DWORD dst_unused:UNUSED_PAD src0_sel:DWORD src1_sel:WORD_1
	v_or_b32_sdwa v114, v23, v21 dst_sel:DWORD dst_unused:UNUSED_PAD src0_sel:DWORD src1_sel:WORD_1
	v_and_b32_sdwa v22, v11, v238 dst_sel:DWORD dst_unused:UNUSED_PAD src0_sel:WORD_1 src1_sel:DWORD
	v_and_b32_sdwa v23, v9, v238 dst_sel:DWORD dst_unused:UNUSED_PAD src0_sel:WORD_1 src1_sel:DWORD
	v_and_b32_sdwa v20, v10, v238 dst_sel:DWORD dst_unused:UNUSED_PAD src0_sel:WORD_1 src1_sel:DWORD
	v_and_b32_sdwa v21, v8, v238 dst_sel:DWORD dst_unused:UNUSED_PAD src0_sel:WORD_1 src1_sel:DWORD
	v_add3_u32 v22, v11, v22, s31
	v_add3_u32 v23, v9, v23, s31
	v_add3_u32 v21, v8, v21, s31
	v_add3_u32 v20, v10, v20, s31
	v_and_b32_e32 v22, 0xffff0000, v22
	v_and_b32_e32 v23, 0xffff0000, v23
	v_or_b32_sdwa v117, v22, v20 dst_sel:DWORD dst_unused:UNUSED_PAD src0_sel:DWORD src1_sel:WORD_1
	v_or_b32_sdwa v116, v23, v21 dst_sel:DWORD dst_unused:UNUSED_PAD src0_sel:DWORD src1_sel:WORD_1
	v_and_b32_sdwa v22, v15, v238 dst_sel:DWORD dst_unused:UNUSED_PAD src0_sel:WORD_1 src1_sel:DWORD
	v_and_b32_sdwa v23, v13, v238 dst_sel:DWORD dst_unused:UNUSED_PAD src0_sel:WORD_1 src1_sel:DWORD
	v_and_b32_sdwa v20, v14, v238 dst_sel:DWORD dst_unused:UNUSED_PAD src0_sel:WORD_1 src1_sel:DWORD
	v_and_b32_sdwa v21, v12, v238 dst_sel:DWORD dst_unused:UNUSED_PAD src0_sel:WORD_1 src1_sel:DWORD
	v_add3_u32 v22, v15, v22, s31
	v_add3_u32 v23, v13, v23, s31
	v_add3_u32 v21, v12, v21, s31
	v_add3_u32 v20, v14, v20, s31
	v_and_b32_e32 v22, 0xffff0000, v22
	v_and_b32_e32 v23, 0xffff0000, v23
	v_or_b32_sdwa v119, v22, v20 dst_sel:DWORD dst_unused:UNUSED_PAD src0_sel:DWORD src1_sel:WORD_1
	v_or_b32_sdwa v118, v23, v21 dst_sel:DWORD dst_unused:UNUSED_PAD src0_sel:DWORD src1_sel:WORD_1
	s_waitcnt vmcnt(0)
	v_mfma_f32_32x32x16_bf16 v[16:31], v[16:19], v[112:115], 0
	v_mfma_f32_32x32x16_bf16 v[16:31], v[32:35], v[116:119], v[16:31]
	v_cndmask_b32_e64 v32, 0, 1, s[38:39]
	v_cmp_ne_u32_e64 s[4:5], 1, v32
	v_cndmask_b32_e64 v32, 0, 1, s[44:45]
	v_cmp_ne_u32_e64 s[10:11], 1, v32
	s_cbranch_vccnz .LBB0_720
	s_and_b64 vcc, exec, s[10:11]
	s_mov_b64 s[6:7], -1
	s_cbranch_vccnz .LBB0_717
	s_mov_b64 s[54:55], -1
	s_mov_b64 s[6:7], 0
	s_cmp_lt_i32 s65, 2
	s_mov_b64 s[8:9], 0
	s_cbranch_scc1 .LBB0_712
	s_cmp_eq_u32 s65, 2
	s_mov_b64 s[8:9], -1
	s_cbranch_scc0 .LBB0_709
	s_mov_b64 s[8:9], 0
	s_nop 2
	v_mfma_f32_32x32x16_bf16 v[16:31], v[54:57], v[76:79], v[16:31]

.LBB0_711:
	s_nop 2
	v_mfma_f32_32x32x16_bf16 v[16:31], v[54:57], v[80:83], v[16:31]
	s_cbranch_execz .LBB0_715
	s_branch .LBB0_716

.LBB0_715:
	s_nop 2
	v_mfma_f32_32x32x16_bf16 v[16:31], v[54:57], v[72:75], v[16:31]

.LBB0_717:
	s_and_b64 vcc, exec, s[6:7]
	s_cbranch_vccz .LBB0_719
	v_mfma_f32_32x32x16_bf16 v[16:31], v[54:57], v[108:111], v[16:31]
	s_nop 11
.LBB0_719:
	s_nop 8
.LBB0_720:
	s_nop 6
	ds_write2st64_b32 v236, v16, v17 offset1:1
	ds_write2st64_b32 v236, v18, v19 offset0:2 offset1:3
	ds_write2st64_b32 v236, v20, v21 offset0:4 offset1:5
	ds_write2st64_b32 v236, v22, v23 offset0:6 offset1:7
	ds_write2st64_b32 v236, v24, v25 offset0:8 offset1:9
	ds_write2st64_b32 v236, v26, v27 offset0:10 offset1:11
	ds_write2st64_b32 v236, v28, v29 offset0:12 offset1:13
	ds_write2st64_b32 v236, v30, v31 offset0:14 offset1:15
	v_mfma_f32_32x32x16_bf16 v[16:31], v[100:103], v[112:115], 0
	v_cndmask_b32_e64 v32, 0, 1, s[40:41]
	v_cmp_ne_u32_e64 s[6:7], 1, v32
	s_andn2_b64 vcc, exec, s[40:41]
	v_mfma_f32_32x32x16_bf16 v[16:31], v[104:107], v[116:119], v[16:31]
	s_cbranch_vccnz .LBB0_736
	s_and_b64 vcc, exec, s[10:11]
	s_mov_b64 s[8:9], -1
	s_cbranch_vccnz .LBB0_733
	s_mov_b64 s[56:57], -1
	s_mov_b64 s[8:9], 0
	s_cmp_lt_i32 s65, 2
	s_mov_b64 s[54:55], 0
	s_cbranch_scc1 .LBB0_728
	s_cmp_eq_u32 s65, 2
	s_mov_b64 s[54:55], -1
	s_cbranch_scc0 .LBB0_725
	s_mov_b64 s[54:55], 0
	s_nop 2
	v_mfma_f32_32x32x16_bf16 v[16:31], v[54:57], v[76:79], v[16:31]

.LBB0_733:
	s_and_b64 vcc, exec, s[8:9]
	s_cbranch_vccz .LBB0_735
	s_nop 3
	v_mfma_f32_32x32x16_bf16 v[16:31], v[54:57], v[108:111], v[16:31]
	s_nop 11
.LBB0_735:
	s_nop 8
.LBB0_736:
	v_pk_mul_f32 v[14:15], v[14:15], v[98:99]
	v_pk_mul_f32 v[10:11], v[10:11], v[90:91]
	v_pk_mul_f32 v[6:7], v[6:7], v[86:87]
	v_pk_mul_f32 v[2:3], v[2:3], v[94:95]
	v_pk_mul_f32 v[0:1], v[0:1], v[92:93]
	v_pk_mul_f32 v[12:13], v[12:13], v[96:97]
	v_pk_mul_f32 v[8:9], v[8:9], v[88:89]
	v_pk_mul_f32 v[4:5], v[4:5], v[84:85]
	s_nop 2
	ds_write2st64_b32 v236, v16, v17 offset0:16 offset1:17
	ds_write2st64_b32 v236, v18, v19 offset0:18 offset1:19
	ds_write2st64_b32 v236, v20, v21 offset0:20 offset1:21
	ds_write2st64_b32 v236, v22, v23 offset0:22 offset1:23
	ds_write2st64_b32 v236, v24, v25 offset0:24 offset1:25
	ds_write2st64_b32 v236, v26, v27 offset0:26 offset1:27
	ds_write2st64_b32 v236, v28, v29 offset0:28 offset1:29
	ds_write2st64_b32 v236, v30, v31 offset0:30 offset1:31
	v_mfma_f32_32x32x16_bf16 v[0:15], v[68:71], v[108:111], v[0:15]
	v_add_co_u32_e32 v20, vcc, s74, v128
	s_mov_b32 s8, 0x14000
	s_nop 0
	v_addc_co_u32_e32 v21, vcc, 0, v129, vcc
	global_load_dwordx4 v[16:19], v[20:21], off
	global_load_dwordx4 v[32:35], v[20:21], off offset:1024
	v_add_co_u32_e32 v20, vcc, s8, v128
	v_mfma_f32_32x32x16_bf16 v[0:15], v[50:53], v[72:75], v[0:15]
	s_nop 0
	v_addc_co_u32_e32 v21, vcc, 0, v129, vcc
	s_movk_i32 s8, 0x4000
	global_load_dwordx4 v[100:103], v[20:21], off
	global_load_dwordx4 v[104:107], v[20:21], off offset:1024
	v_add_co_u32_e32 v20, vcc, s8, v130
	v_mfma_f32_32x32x16_bf16 v[0:15], v[60:63], v[76:79], v[0:15]
	s_nop 0
	v_addc_co_u32_e32 v21, vcc, 0, v131, vcc
	global_load_dwordx4 v[56:59], v[20:21], off
	v_add_co_u32_e32 v20, vcc, s74, v124
	s_nop 1
	v_addc_co_u32_e32 v21, vcc, 0, v125, vcc
	v_mfma_f32_32x32x16_bf16 v[0:15], v[64:67], v[80:83], v[0:15]
	global_load_dwordx4 v[84:87], v[20:21], off
	global_load_dwordx4 v[60:63], v[20:21], off offset:1024
	global_load_dwordx4 v[64:67], v[20:21], off offset:2048
	global_load_dwordx4 v[68:71], v[20:21], off offset:3072
	global_load_dwordx4 v[116:119], v[126:127], off offset:2048
	global_load_dwordx4 v[92:95], v[126:127], off offset:2080
	global_load_dwordx4 v[112:115], v[126:127], off offset:2112
	global_load_dwordx4 v[120:123], v[126:127], off offset:2144
	v_add_co_u32_e32 v20, vcc, 0x20000, v132
	s_nop 1
	v_addc_co_u32_e32 v21, vcc, 0, v133, vcc
	global_load_dwordx4 v[88:91], v[20:21], off
	global_load_dwordx4 v[72:75], v[20:21], off offset:1024
	global_load_dwordx4 v[76:79], v[20:21], off offset:2048
	global_load_dwordx4 v[80:83], v[20:21], off offset:3072
	v_cndmask_b32_e64 v20, 0, 1, s[42:43]
	v_cmp_ne_u32_e64 s[8:9], 1, v20
	s_andn2_b64 vcc, exec, s[42:43]
	s_cbranch_vccnz .LBB0_738
	s_add_u32 s54, s12, s46
	s_addc_u32 s55, s13, s47
	v_lshl_add_u64 v[20:21], s[54:55], 0, v[138:139]
	v_add_co_u32_e32 v20, vcc, 0x30000, v20
	s_nop 1
	v_addc_co_u32_e32 v21, vcc, 0, v21, vcc
	global_load_dwordx4 v[52:55], v[20:21], off nt
	s_branch .LBB0_739

.LBB0_739:
	s_waitcnt lgkmcnt(0)
	s_barrier
	ds_read2st64_b32 v[20:21], v239 offset1:1
	ds_read2st64_b32 v[22:23], v239 offset0:32 offset1:33
	ds_read2st64_b32 v[24:25], v239 offset0:64 offset1:65
	ds_read2st64_b32 v[26:27], v239 offset0:96 offset1:97
	s_ashr_i32 s78, s80, 6
	s_lshl_b32 s54, s78, 11
	ds_read2st64_b32 v[28:29], v239 offset0:128 offset1:129
	ds_read2st64_b32 v[30:31], v239 offset0:160 offset1:161
	ds_read2st64_b32 v[36:37], v239 offset0:192 offset1:193
	ds_read2st64_b32 v[38:39], v239 offset0:224 offset1:225
	s_ashr_i32 s55, s54, 31
	s_waitcnt lgkmcnt(7)
	v_add_f32_e32 v20, 0, v20
	s_and_b32 s79, s81, 3
	s_lshl_b64 s[54:55], s[54:55], 12
	s_waitcnt lgkmcnt(6)
	v_add_f32_e32 v20, v20, v22
	s_add_u32 s56, s72, s54
	s_waitcnt lgkmcnt(5)
	v_add_f32_e32 v20, v20, v24
	s_addc_u32 s57, s73, s55
	s_lshl_b32 s58, s79, 10
	s_waitcnt lgkmcnt(4)
	v_add_f32_e32 v20, v20, v26
	s_add_u32 s56, s56, s58
	s_waitcnt lgkmcnt(3)
	v_add_f32_e32 v20, v20, v28
	s_addc_u32 s57, s57, 0
	s_lshl_b32 s84, s82, 6
	s_waitcnt lgkmcnt(2)
	v_add_f32_e32 v20, v20, v30
	s_add_u32 s56, s56, s84
	s_waitcnt lgkmcnt(1)
	v_add_f32_e32 v20, v20, v36
	s_addc_u32 s57, s57, 0
	v_lshlrev_b32_e32 v48, 1, v140
	s_waitcnt lgkmcnt(0)
	v_add_f32_e32 v20, v20, v38
	v_lshl_add_u64 v[132:133], s[56:57], 0, v[48:49]
	v_bfe_u32 v22, v20, 16, 1
	v_add3_u32 v20, v20, v22, s31
	v_lshl_add_u64 v[40:41], v[132:133], 0, v[144:145]
	global_store_short_d16_hi v[40:41], v20, off
	v_add_f32_e32 v20, 0, v21
	v_add_f32_e32 v20, v20, v23
	v_add_f32_e32 v20, v20, v25
	v_add_f32_e32 v20, v20, v27
	v_add_f32_e32 v20, v20, v29
	v_add_f32_e32 v20, v20, v31
	v_add_f32_e32 v20, v20, v37
	v_add_f32_e32 v20, v20, v39
	v_bfe_u32 v21, v20, 16, 1
	v_add3_u32 v22, v20, v21, s31
	v_lshl_add_u64 v[20:21], v[132:133], 0, v[146:147]
	global_store_short_d16_hi v[20:21], v22, off
	ds_read2st64_b32 v[20:21], v239 offset0:2 offset1:3
	ds_read2st64_b32 v[22:23], v239 offset0:34 offset1:35
	ds_read2st64_b32 v[24:25], v239 offset0:66 offset1:67
	ds_read2st64_b32 v[26:27], v239 offset0:98 offset1:99
	ds_read2st64_b32 v[28:29], v239 offset0:130 offset1:131
	ds_read2st64_b32 v[30:31], v239 offset0:162 offset1:163
	ds_read2st64_b32 v[36:37], v239 offset0:194 offset1:195
	ds_read2st64_b32 v[38:39], v239 offset0:226 offset1:227
	s_waitcnt lgkmcnt(7)
	v_add_f32_e32 v20, 0, v20
	s_waitcnt lgkmcnt(6)
	v_add_f32_e32 v20, v20, v22
	s_waitcnt lgkmcnt(5)
	v_add_f32_e32 v20, v20, v24
	s_waitcnt lgkmcnt(4)
	v_add_f32_e32 v20, v20, v26
	s_waitcnt lgkmcnt(3)
	v_add_f32_e32 v20, v20, v28
	s_waitcnt lgkmcnt(2)
	v_add_f32_e32 v20, v20, v30
	s_waitcnt lgkmcnt(1)
	v_add_f32_e32 v20, v20, v36
	s_waitcnt lgkmcnt(0)
	v_add_f32_e32 v20, v20, v38
	v_bfe_u32 v22, v20, 16, 1
	v_add3_u32 v20, v20, v22, s31
	v_lshl_add_u64 v[40:41], v[132:133], 0, v[148:149]
	global_store_short_d16_hi v[40:41], v20, off
	v_add_f32_e32 v20, 0, v21
	v_add_f32_e32 v20, v20, v23
	v_add_f32_e32 v20, v20, v25
	v_add_f32_e32 v20, v20, v27
	v_add_f32_e32 v20, v20, v29
	v_add_f32_e32 v20, v20, v31
	v_add_f32_e32 v20, v20, v37
	v_add_f32_e32 v20, v20, v39
	v_bfe_u32 v21, v20, 16, 1
	v_add3_u32 v22, v20, v21, s31
	v_lshl_add_u64 v[20:21], v[132:133], 0, v[150:151]
	global_store_short_d16_hi v[20:21], v22, off
	v_and_b32_sdwa v22, v3, v238 dst_sel:DWORD dst_unused:UNUSED_PAD src0_sel:WORD_1 src1_sel:DWORD
	v_and_b32_sdwa v23, v1, v238 dst_sel:DWORD dst_unused:UNUSED_PAD src0_sel:WORD_1 src1_sel:DWORD
	v_and_b32_sdwa v20, v2, v238 dst_sel:DWORD dst_unused:UNUSED_PAD src0_sel:WORD_1 src1_sel:DWORD
	v_and_b32_sdwa v21, v0, v238 dst_sel:DWORD dst_unused:UNUSED_PAD src0_sel:WORD_1 src1_sel:DWORD
	v_add3_u32 v22, v3, v22, s31
	v_add3_u32 v23, v1, v23, s31
	v_add3_u32 v21, v0, v21, s31
	v_add3_u32 v20, v2, v20, s31
	v_and_b32_e32 v22, 0xffff0000, v22
	v_and_b32_e32 v23, 0xffff0000, v23
	v_or_b32_sdwa v97, v22, v20 dst_sel:DWORD dst_unused:UNUSED_PAD src0_sel:DWORD src1_sel:WORD_1
	v_or_b32_sdwa v96, v23, v21 dst_sel:DWORD dst_unused:UNUSED_PAD src0_sel:DWORD src1_sel:WORD_1
	v_and_b32_sdwa v22, v7, v238 dst_sel:DWORD dst_unused:UNUSED_PAD src0_sel:WORD_1 src1_sel:DWORD
	v_and_b32_sdwa v23, v5, v238 dst_sel:DWORD dst_unused:UNUSED_PAD src0_sel:WORD_1 src1_sel:DWORD
	v_and_b32_sdwa v20, v6, v238 dst_sel:DWORD dst_unused:UNUSED_PAD src0_sel:WORD_1 src1_sel:DWORD
	v_and_b32_sdwa v21, v4, v238 dst_sel:DWORD dst_unused:UNUSED_PAD src0_sel:WORD_1 src1_sel:DWORD
	v_add3_u32 v22, v7, v22, s31
	v_add3_u32 v23, v5, v23, s31
	v_add3_u32 v21, v4, v21, s31
	v_add3_u32 v20, v6, v20, s31
	v_and_b32_e32 v22, 0xffff0000, v22
	v_and_b32_e32 v23, 0xffff0000, v23
	v_or_b32_sdwa v99, v22, v20 dst_sel:DWORD dst_unused:UNUSED_PAD src0_sel:DWORD src1_sel:WORD_1
	v_or_b32_sdwa v98, v23, v21 dst_sel:DWORD dst_unused:UNUSED_PAD src0_sel:DWORD src1_sel:WORD_1
	v_and_b32_sdwa v22, v11, v238 dst_sel:DWORD dst_unused:UNUSED_PAD src0_sel:WORD_1 src1_sel:DWORD
	v_and_b32_sdwa v23, v9, v238 dst_sel:DWORD dst_unused:UNUSED_PAD src0_sel:WORD_1 src1_sel:DWORD
	v_and_b32_sdwa v20, v10, v238 dst_sel:DWORD dst_unused:UNUSED_PAD src0_sel:WORD_1 src1_sel:DWORD
	v_and_b32_sdwa v21, v8, v238 dst_sel:DWORD dst_unused:UNUSED_PAD src0_sel:WORD_1 src1_sel:DWORD
	v_add3_u32 v22, v11, v22, s31
	v_add3_u32 v23, v9, v23, s31
	v_add3_u32 v21, v8, v21, s31
	v_add3_u32 v20, v10, v20, s31
	v_and_b32_e32 v22, 0xffff0000, v22
	v_and_b32_e32 v23, 0xffff0000, v23
	v_or_b32_sdwa v109, v22, v20 dst_sel:DWORD dst_unused:UNUSED_PAD src0_sel:DWORD src1_sel:WORD_1
	v_or_b32_sdwa v108, v23, v21 dst_sel:DWORD dst_unused:UNUSED_PAD src0_sel:DWORD src1_sel:WORD_1
	v_and_b32_sdwa v22, v15, v238 dst_sel:DWORD dst_unused:UNUSED_PAD src0_sel:WORD_1 src1_sel:DWORD
	v_and_b32_sdwa v23, v13, v238 dst_sel:DWORD dst_unused:UNUSED_PAD src0_sel:WORD_1 src1_sel:DWORD
	v_and_b32_sdwa v20, v14, v238 dst_sel:DWORD dst_unused:UNUSED_PAD src0_sel:WORD_1 src1_sel:DWORD
	v_and_b32_sdwa v21, v12, v238 dst_sel:DWORD dst_unused:UNUSED_PAD src0_sel:WORD_1 src1_sel:DWORD
	v_add3_u32 v22, v15, v22, s31
	v_add3_u32 v23, v13, v23, s31
	v_add3_u32 v21, v12, v21, s31
	v_add3_u32 v20, v14, v20, s31
	v_and_b32_e32 v22, 0xffff0000, v22
	v_and_b32_e32 v23, 0xffff0000, v23
	v_or_b32_sdwa v111, v22, v20 dst_sel:DWORD dst_unused:UNUSED_PAD src0_sel:DWORD src1_sel:WORD_1
	v_or_b32_sdwa v110, v23, v21 dst_sel:DWORD dst_unused:UNUSED_PAD src0_sel:DWORD src1_sel:WORD_1
	s_waitcnt vmcnt(20)
	v_mfma_f32_32x32x16_bf16 v[16:31], v[16:19], v[96:99], 0
	s_and_b64 vcc, exec, s[4:5]
	s_waitcnt vmcnt(19)
	v_mfma_f32_32x32x16_bf16 v[16:31], v[32:35], v[108:111], v[16:31]
	s_cbranch_vccnz .LBB0_755
	s_and_b64 vcc, exec, s[10:11]
	s_mov_b64 s[56:57], -1
	s_cbranch_vccnz .LBB0_752
	s_mov_b64 s[60:61], -1
	s_mov_b64 s[56:57], 0
	s_cmp_lt_i32 s65, 2
	s_mov_b64 s[58:59], 0
	s_cbranch_scc1 .LBB0_747
	s_cmp_eq_u32 s65, 2
	s_mov_b64 s[58:59], -1
	s_cbranch_scc0 .LBB0_744
	s_mov_b64 s[58:59], 0
	s_waitcnt vmcnt(5)
	s_nop 2
	v_mfma_f32_32x32x16_bf16 v[16:31], v[56:59], v[76:79], v[16:31]

.LBB0_746:
	s_waitcnt vmcnt(4)
	s_nop 2
	v_mfma_f32_32x32x16_bf16 v[16:31], v[56:59], v[80:83], v[16:31]
	s_cbranch_execz .LBB0_750
	s_branch .LBB0_751

.LBB0_750:
	s_waitcnt vmcnt(6)
	s_nop 2
	v_mfma_f32_32x32x16_bf16 v[16:31], v[56:59], v[72:75], v[16:31]

.LBB0_752:
	s_and_b64 vcc, exec, s[56:57]
	s_cbranch_vccz .LBB0_754
	s_waitcnt vmcnt(7)
	s_nop 2
	v_mfma_f32_32x32x16_bf16 v[16:31], v[56:59], v[88:91], v[16:31]
	s_nop 11
.LBB0_754:
	s_nop 8
.LBB0_755:
	s_nop 10
	ds_write2st64_b32 v237, v16, v17 offset1:1
	ds_write2st64_b32 v237, v18, v19 offset0:2 offset1:3
	ds_write2st64_b32 v237, v20, v21 offset0:4 offset1:5
	ds_write2st64_b32 v237, v22, v23 offset0:6 offset1:7
	ds_write2st64_b32 v237, v24, v25 offset0:8 offset1:9
	ds_write2st64_b32 v237, v26, v27 offset0:10 offset1:11
	ds_write2st64_b32 v237, v28, v29 offset0:12 offset1:13
	ds_write2st64_b32 v237, v30, v31 offset0:14 offset1:15
	s_waitcnt vmcnt(18)
	v_mfma_f32_32x32x16_bf16 v[16:31], v[100:103], v[96:99], 0
	s_and_b64 vcc, exec, s[6:7]
	s_waitcnt vmcnt(17)
	v_mfma_f32_32x32x16_bf16 v[16:31], v[104:107], v[108:111], v[16:31]
	s_cbranch_vccnz .LBB0_771
	s_and_b64 vcc, exec, s[10:11]
	s_mov_b64 s[10:11], -1
	s_cbranch_vccnz .LBB0_768
	s_mov_b64 s[58:59], -1
	s_mov_b64 s[10:11], 0
	s_cmp_lt_i32 s65, 2
	s_mov_b64 s[56:57], 0
	s_cbranch_scc1 .LBB0_763
	s_cmp_eq_u32 s65, 2
	s_mov_b64 s[56:57], -1
	s_cbranch_scc0 .LBB0_760
	s_mov_b64 s[56:57], 0
	s_waitcnt vmcnt(5)
	s_nop 2
	v_mfma_f32_32x32x16_bf16 v[16:31], v[56:59], v[76:79], v[16:31]

.LBB0_768:
	s_and_b64 vcc, exec, s[10:11]
	s_cbranch_vccz .LBB0_770
	s_waitcnt vmcnt(7)
	s_nop 2
	v_mfma_f32_32x32x16_bf16 v[16:31], v[56:59], v[88:91], v[16:31]
	s_nop 11
.LBB0_770:
	s_nop 8
.LBB0_771:
	s_waitcnt vmcnt(8)
	v_pk_mul_f32 v[14:15], v[14:15], v[122:123]
	v_pk_mul_f32 v[10:11], v[10:11], v[114:115]
	v_pk_mul_f32 v[6:7], v[6:7], v[94:95]
	v_pk_mul_f32 v[2:3], v[2:3], v[118:119]
	v_pk_mul_f32 v[0:1], v[0:1], v[116:117]
	v_pk_mul_f32 v[12:13], v[12:13], v[120:121]
	v_pk_mul_f32 v[8:9], v[8:9], v[112:113]
	v_pk_mul_f32 v[4:5], v[4:5], v[92:93]
	s_mov_b32 s10, 0x18000
	s_nop 0
	ds_write2st64_b32 v237, v16, v17 offset0:16 offset1:17
	ds_write2st64_b32 v237, v18, v19 offset0:18 offset1:19
	ds_write2st64_b32 v237, v20, v21 offset0:20 offset1:21
	ds_write2st64_b32 v237, v22, v23 offset0:22 offset1:23
	ds_write2st64_b32 v237, v24, v25 offset0:24 offset1:25
	ds_write2st64_b32 v237, v26, v27 offset0:26 offset1:27
	ds_write2st64_b32 v237, v28, v29 offset0:28 offset1:29
	ds_write2st64_b32 v237, v30, v31 offset0:30 offset1:31
	s_waitcnt vmcnt(7)
	v_mfma_f32_32x32x16_bf16 v[0:15], v[84:87], v[88:91], v[0:15]
	v_add_co_u32_e32 v16, vcc, s10, v128
	s_mov_b32 s10, 0x1c000
	s_nop 0
	v_addc_co_u32_e32 v17, vcc, 0, v129, vcc
	global_load_dwordx4 v[104:107], v[16:17], off
	global_load_dwordx4 v[108:111], v[16:17], off offset:1024
	v_add_co_u32_e32 v16, vcc, s10, v128
	s_waitcnt vmcnt(8)
	v_mfma_f32_32x32x16_bf16 v[0:15], v[60:63], v[72:75], v[0:15]
	v_addc_co_u32_e32 v17, vcc, 0, v129, vcc
	s_movk_i32 s10, 0x6000
	global_load_dwordx4 v[96:99], v[16:17], off
	global_load_dwordx4 v[100:103], v[16:17], off offset:1024
	v_add_co_u32_e32 v16, vcc, s10, v130
	s_waitcnt vmcnt(9)
	v_mfma_f32_32x32x16_bf16 v[0:15], v[64:67], v[76:79], v[0:15]
	v_addc_co_u32_e32 v17, vcc, 0, v131, vcc
	global_load_dwordx4 v[56:59], v[16:17], off
	v_add_co_u32_e32 v16, vcc, 0x18000, v124
	s_nop 1
	v_addc_co_u32_e32 v17, vcc, 0, v125, vcc
	s_waitcnt vmcnt(9)
	v_mfma_f32_32x32x16_bf16 v[0:15], v[68:71], v[80:83], v[0:15]
	global_load_dwordx4 v[72:75], v[16:17], off
	global_load_dwordx4 v[68:71], v[16:17], off offset:1024
	global_load_dwordx4 v[64:67], v[16:17], off offset:2048
	global_load_dwordx4 v[60:63], v[16:17], off offset:3072
	global_load_dwordx4 v[84:87], v[126:127], off offset:3072
	global_load_dwordx4 v[76:79], v[126:127], off offset:3104
	global_load_dwordx4 v[88:91], v[126:127], off offset:3136
	global_load_dwordx4 v[92:95], v[126:127], off offset:3168
	s_and_b64 vcc, exec, s[8:9]
	s_cbranch_vccnz .LBB0_773
	s_add_u32 s10, s12, s46
	s_addc_u32 s11, s13, s47
	v_lshl_add_u64 v[16:17], s[10:11], 0, v[138:139]
	v_add_co_u32_e32 v16, vcc, 0x40000, v16
	s_nop 1
	v_addc_co_u32_e32 v17, vcc, 0, v17, vcc
	global_load_dwordx4 v[80:83], v[16:17], off nt
	s_and_b64 vcc, exec, s[8:9]
	s_cbranch_vccz .LBB0_774
	s_branch .LBB0_775

.LBB0_777:
	s_mul_i32 s10, s80, 0xab
	s_bfe_u32 s10, s10, 0x70009
	s_mul_i32 s10, s10, 3
	s_sub_i32 s10, s80, s10
	s_and_b32 s10, s10, 0xff
	v_lshl_add_u32 v16, s10, 12, v137
	v_and_b32_sdwa v18, v3, v238 dst_sel:DWORD dst_unused:UNUSED_PAD src0_sel:WORD_1 src1_sel:DWORD
	v_and_b32_sdwa v19, v1, v238 dst_sel:DWORD dst_unused:UNUSED_PAD src0_sel:WORD_1 src1_sel:DWORD
	ds_read_b128 v[124:127], v16
	ds_read_b128 v[120:123], v16 offset:1024
	ds_read_b128 v[116:119], v16 offset:2048
	ds_read_b128 v[112:115], v16 offset:3072
	v_and_b32_sdwa v16, v2, v238 dst_sel:DWORD dst_unused:UNUSED_PAD src0_sel:WORD_1 src1_sel:DWORD
	v_and_b32_sdwa v17, v0, v238 dst_sel:DWORD dst_unused:UNUSED_PAD src0_sel:WORD_1 src1_sel:DWORD
	v_add3_u32 v18, v3, v18, s31
	v_add3_u32 v19, v1, v19, s31
	v_add3_u32 v17, v0, v17, s31
	v_add3_u32 v16, v2, v16, s31
	v_and_b32_e32 v18, 0xffff0000, v18
	v_and_b32_e32 v19, 0xffff0000, v19
	v_or_b32_sdwa v129, v18, v16 dst_sel:DWORD dst_unused:UNUSED_PAD src0_sel:DWORD src1_sel:WORD_1
	v_or_b32_sdwa v128, v19, v17 dst_sel:DWORD dst_unused:UNUSED_PAD src0_sel:DWORD src1_sel:WORD_1
	v_and_b32_sdwa v18, v7, v238 dst_sel:DWORD dst_unused:UNUSED_PAD src0_sel:WORD_1 src1_sel:DWORD
	v_and_b32_sdwa v19, v5, v238 dst_sel:DWORD dst_unused:UNUSED_PAD src0_sel:WORD_1 src1_sel:DWORD
	v_and_b32_sdwa v16, v6, v238 dst_sel:DWORD dst_unused:UNUSED_PAD src0_sel:WORD_1 src1_sel:DWORD
	v_and_b32_sdwa v17, v4, v238 dst_sel:DWORD dst_unused:UNUSED_PAD src0_sel:WORD_1 src1_sel:DWORD
	v_add3_u32 v18, v7, v18, s31
	v_add3_u32 v19, v5, v19, s31
	v_add3_u32 v17, v4, v17, s31
	v_add3_u32 v16, v6, v16, s31
	v_and_b32_e32 v18, 0xffff0000, v18
	v_and_b32_e32 v19, 0xffff0000, v19
	v_or_b32_sdwa v131, v18, v16 dst_sel:DWORD dst_unused:UNUSED_PAD src0_sel:DWORD src1_sel:WORD_1
	v_or_b32_sdwa v130, v19, v17 dst_sel:DWORD dst_unused:UNUSED_PAD src0_sel:DWORD src1_sel:WORD_1
	v_and_b32_sdwa v18, v11, v238 dst_sel:DWORD dst_unused:UNUSED_PAD src0_sel:WORD_1 src1_sel:DWORD
	v_and_b32_sdwa v19, v9, v238 dst_sel:DWORD dst_unused:UNUSED_PAD src0_sel:WORD_1 src1_sel:DWORD
	v_and_b32_sdwa v16, v10, v238 dst_sel:DWORD dst_unused:UNUSED_PAD src0_sel:WORD_1 src1_sel:DWORD
	v_and_b32_sdwa v17, v8, v238 dst_sel:DWORD dst_unused:UNUSED_PAD src0_sel:WORD_1 src1_sel:DWORD
	v_add3_u32 v18, v11, v18, s31
	v_add3_u32 v19, v9, v19, s31
	v_add3_u32 v17, v8, v17, s31
	v_add3_u32 v16, v10, v16, s31
	v_and_b32_e32 v18, 0xffff0000, v18
	v_and_b32_e32 v19, 0xffff0000, v19
	v_or_b32_sdwa v133, v18, v16 dst_sel:DWORD dst_unused:UNUSED_PAD src0_sel:DWORD src1_sel:WORD_1
	v_or_b32_sdwa v132, v19, v17 dst_sel:DWORD dst_unused:UNUSED_PAD src0_sel:DWORD src1_sel:WORD_1
	v_and_b32_sdwa v18, v15, v238 dst_sel:DWORD dst_unused:UNUSED_PAD src0_sel:WORD_1 src1_sel:DWORD
	v_and_b32_sdwa v19, v13, v238 dst_sel:DWORD dst_unused:UNUSED_PAD src0_sel:WORD_1 src1_sel:DWORD
	v_and_b32_sdwa v16, v14, v238 dst_sel:DWORD dst_unused:UNUSED_PAD src0_sel:WORD_1 src1_sel:DWORD
	v_and_b32_sdwa v17, v12, v238 dst_sel:DWORD dst_unused:UNUSED_PAD src0_sel:WORD_1 src1_sel:DWORD
	v_add3_u32 v18, v15, v18, s31
	v_add3_u32 v19, v13, v19, s31
	v_add3_u32 v17, v12, v17, s31
	v_add3_u32 v16, v14, v16, s31
	v_and_b32_e32 v18, 0xffff0000, v18
	v_and_b32_e32 v19, 0xffff0000, v19
	v_or_b32_sdwa v135, v18, v16 dst_sel:DWORD dst_unused:UNUSED_PAD src0_sel:DWORD src1_sel:WORD_1
	v_or_b32_sdwa v134, v19, v17 dst_sel:DWORD dst_unused:UNUSED_PAD src0_sel:DWORD src1_sel:WORD_1
	s_waitcnt vmcnt(16)
	v_mfma_f32_32x32x16_bf16 v[16:31], v[104:107], v[128:131], 0
	s_and_b64 vcc, exec, s[4:5]
	s_waitcnt vmcnt(7)
	v_mfma_f32_32x32x16_bf16 v[16:31], v[108:111], v[132:135], v[16:31]
	s_cbranch_vccnz .LBB0_793
	s_mov_b64 s[10:11], -1
	s_and_b64 vcc, exec, s[44:45]
	s_cbranch_vccz .LBB0_790
	s_mov_b64 s[54:55], -1
	s_mov_b64 s[10:11], 0
	s_cmp_lt_i32 s65, 2
	s_mov_b64 s[12:13], 0
	s_cbranch_scc1 .LBB0_785
	s_cmp_eq_u32 s65, 2
	s_mov_b64 s[12:13], -1
	s_cbranch_scc0 .LBB0_782
	s_mov_b64 s[12:13], 0
	s_waitcnt vmcnt(4) lgkmcnt(1)
	s_nop 2
	v_mfma_f32_32x32x16_bf16 v[16:31], v[56:59], v[116:119], v[16:31]

.LBB0_784:
	s_waitcnt vmcnt(4) lgkmcnt(0)
	s_nop 2
	v_mfma_f32_32x32x16_bf16 v[16:31], v[56:59], v[112:115], v[16:31]
	s_cbranch_execz .LBB0_788
	s_branch .LBB0_789

.LBB0_788:
	s_waitcnt vmcnt(4) lgkmcnt(2)
	s_nop 2
	v_mfma_f32_32x32x16_bf16 v[16:31], v[56:59], v[120:123], v[16:31]

.LBB0_790:
	s_and_b64 vcc, exec, s[10:11]
	s_cbranch_vccz .LBB0_792
	s_waitcnt vmcnt(4) lgkmcnt(3)
	s_nop 2
	v_mfma_f32_32x32x16_bf16 v[16:31], v[56:59], v[124:127], v[16:31]
	s_nop 11
.LBB0_792:
	s_nop 8
.LBB0_793:
	s_nop 10
	ds_write2st64_b32 v236, v16, v17 offset1:1
	ds_write2st64_b32 v236, v18, v19 offset0:2 offset1:3
	ds_write2st64_b32 v236, v20, v21 offset0:4 offset1:5
	ds_write2st64_b32 v236, v22, v23 offset0:6 offset1:7
	ds_write2st64_b32 v236, v24, v25 offset0:8 offset1:9
	ds_write2st64_b32 v236, v26, v27 offset0:10 offset1:11
	ds_write2st64_b32 v236, v28, v29 offset0:12 offset1:13
	ds_write2st64_b32 v236, v30, v31 offset0:14 offset1:15
	s_waitcnt vmcnt(6)
	v_mfma_f32_32x32x16_bf16 v[16:31], v[96:99], v[128:131], 0
	s_and_b64 vcc, exec, s[6:7]
	s_waitcnt vmcnt(5)
	v_mfma_f32_32x32x16_bf16 v[16:31], v[100:103], v[132:135], v[16:31]
	s_cbranch_vccnz .LBB0_809
	s_mov_b64 s[10:11], -1
	s_and_b64 vcc, exec, s[44:45]
	s_cbranch_vccz .LBB0_806
	s_mov_b64 s[54:55], -1
	s_mov_b64 s[10:11], 0
	s_cmp_lt_i32 s65, 2
	s_mov_b64 s[12:13], 0
	s_cbranch_scc1 .LBB0_801
	s_cmp_eq_u32 s65, 2
	s_mov_b64 s[12:13], -1
	s_cbranch_scc0 .LBB0_798
	s_mov_b64 s[12:13], 0
	s_waitcnt vmcnt(4) lgkmcnt(9)
	s_nop 2
	v_mfma_f32_32x32x16_bf16 v[16:31], v[56:59], v[116:119], v[16:31]

.LBB0_800:
	s_waitcnt vmcnt(4) lgkmcnt(8)
	s_nop 2
	v_mfma_f32_32x32x16_bf16 v[16:31], v[56:59], v[112:115], v[16:31]
	s_cbranch_execz .LBB0_804
	s_branch .LBB0_805

.LBB0_804:
	s_waitcnt vmcnt(4) lgkmcnt(10)
	s_nop 2
	v_mfma_f32_32x32x16_bf16 v[16:31], v[56:59], v[120:123], v[16:31]

.LBB0_806:
	s_and_b64 vcc, exec, s[10:11]
	s_cbranch_vccz .LBB0_808
	s_waitcnt vmcnt(4) lgkmcnt(11)
	s_nop 2
	v_mfma_f32_32x32x16_bf16 v[16:31], v[56:59], v[124:127], v[16:31]
	s_nop 11
.LBB0_808:
	s_nop 8
.LBB0_809:
	s_waitcnt vmcnt(4)
	v_pk_mul_f32 v[14:15], v[14:15], v[94:95]
	v_pk_mul_f32 v[10:11], v[10:11], v[90:91]
	v_pk_mul_f32 v[6:7], v[6:7], v[78:79]
	v_pk_mul_f32 v[2:3], v[2:3], v[86:87]
	v_pk_mul_f32 v[0:1], v[0:1], v[84:85]
	v_pk_mul_f32 v[12:13], v[12:13], v[92:93]
	v_pk_mul_f32 v[8:9], v[8:9], v[88:89]
	v_pk_mul_f32 v[4:5], v[4:5], v[76:77]
	v_lshl_add_u64 v[230:231], s[96:97], 0, v[212:213]
	s_mov_b32 s10, 0x2f520000
	s_waitcnt lgkmcnt(11)
	v_mfma_f32_32x32x16_bf16 v[0:15], v[72:75], v[124:127], v[0:15]
	v_add_co_u32_e32 v32, vcc, s10, v230
	s_mov_b32 s10, 0x2f524000
	s_nop 0
	v_addc_co_u32_e32 v33, vcc, 0, v231, vcc
	global_load_dwordx4 v[104:107], v[32:33], off
	global_load_dwordx4 v[108:111], v[32:33], off offset:1024
	v_add_co_u32_e32 v32, vcc, s10, v230
	s_waitcnt lgkmcnt(10)
	v_mfma_f32_32x32x16_bf16 v[0:15], v[68:71], v[120:123], v[0:15]
	v_addc_co_u32_e32 v33, vcc, 0, v231, vcc
	v_lshl_add_u64 v[232:233], s[96:97], 0, v[210:211]
	s_mov_b32 s10, 0x31608000
	global_load_dwordx4 v[96:99], v[32:33], off
	global_load_dwordx4 v[100:103], v[32:33], off offset:1024
	v_add_co_u32_e32 v32, vcc, s10, v232
	s_waitcnt lgkmcnt(9)
	v_mfma_f32_32x32x16_bf16 v[0:15], v[64:67], v[116:119], v[0:15]
	v_addc_co_u32_e32 v33, vcc, 0, v233, vcc
	v_lshl_add_u64 v[226:227], s[96:97], 0, v[216:217]
	s_mov_b32 s10, 0x305a0000
	v_add_co_u32_e32 v34, vcc, s10, v226
	v_lshl_add_u64 v[228:229], s[96:97], 0, v[214:215]
	s_waitcnt lgkmcnt(8)
	v_mfma_f32_32x32x16_bf16 v[0:15], v[60:63], v[112:115], v[0:15]
	v_addc_co_u32_e32 v35, vcc, 0, v227, vcc
	global_load_dwordx4 v[56:59], v[32:33], off
	global_load_dwordx4 v[72:75], v[34:35], off
	global_load_dwordx4 v[68:71], v[34:35], off offset:1024
	global_load_dwordx4 v[64:67], v[34:35], off offset:2048
	global_load_dwordx4 v[60:63], v[34:35], off offset:3072
	global_load_dwordx4 v[84:87], v[228:229], off offset:-1024
	global_load_dwordx4 v[76:79], v[228:229], off offset:-992
	global_load_dwordx4 v[88:91], v[228:229], off offset:-960
	global_load_dwordx4 v[92:95], v[228:229], off offset:-928
	s_cmp_lt_u32 s80, 31
	s_cselect_b64 s[56:57], -1, 0
	s_cmp_gt_u32 s80, 30
	s_cselect_b64 s[54:55], -1, 0
	s_and_b64 s[12:13], s[42:43], s[56:57]
	ds_write2st64_b32 v236, v16, v17 offset0:16 offset1:17
	ds_write2st64_b32 v236, v18, v19 offset0:18 offset1:19
	ds_write2st64_b32 v236, v20, v21 offset0:20 offset1:21
	ds_write2st64_b32 v236, v22, v23 offset0:22 offset1:23
	ds_write2st64_b32 v236, v24, v25 offset0:24 offset1:25
	ds_write2st64_b32 v236, v26, v27 offset0:26 offset1:27
	ds_write2st64_b32 v236, v28, v29 offset0:28 offset1:29
	ds_write2st64_b32 v236, v30, v31 offset0:30 offset1:31
	v_cndmask_b32_e64 v16, 0, 1, s[12:13]
	v_cmp_ne_u32_e64 s[10:11], 1, v16
	s_andn2_b64 vcc, exec, s[12:13]
	v_lshl_add_u64 v[224:225], s[96:97], 0, v[50:51]
	s_cbranch_vccnz .LBB0_811
	v_add_co_u32_e32 v16, vcc, 0x31a70000, v224
	s_nop 1
	v_addc_co_u32_e32 v17, vcc, 0, v225, vcc
	global_load_dwordx4 v[52:55], v[16:17], off nt

.LBB0_813:
	s_waitcnt lgkmcnt(0)
	s_barrier
	ds_read2st64_b32 v[16:17], v239 offset1:1
	ds_read2st64_b32 v[18:19], v239 offset0:32 offset1:33
	ds_read2st64_b32 v[20:21], v239 offset0:64 offset1:65
	ds_read2st64_b32 v[22:23], v239 offset0:96 offset1:97
	ds_read2st64_b32 v[24:25], v239 offset0:128 offset1:129
	ds_read2st64_b32 v[26:27], v239 offset0:160 offset1:161
	ds_read2st64_b32 v[28:29], v239 offset0:192 offset1:193
	ds_read2st64_b32 v[30:31], v239 offset0:224 offset1:225
	s_waitcnt lgkmcnt(7)
	v_add_f32_e32 v16, 0, v16
	s_waitcnt lgkmcnt(6)
	v_add_f32_e32 v16, v16, v18
	s_waitcnt lgkmcnt(5)
	v_add_f32_e32 v16, v16, v20
	s_waitcnt lgkmcnt(4)
	v_add_f32_e32 v16, v16, v22
	s_waitcnt lgkmcnt(3)
	v_add_f32_e32 v16, v16, v24
	s_waitcnt lgkmcnt(2)
	v_add_f32_e32 v16, v16, v26
	s_waitcnt lgkmcnt(1)
	v_add_f32_e32 v16, v16, v28
	s_waitcnt lgkmcnt(0)
	v_add_f32_e32 v16, v16, v30
	v_bfe_u32 v18, v16, 16, 1
	v_add3_u32 v16, v16, v18, s31
	v_lshl_add_u64 v[32:33], s[96:97], 0, v[222:223]
	global_store_short_d16_hi v[32:33], v16, off
	v_add_f32_e32 v16, 0, v17
	v_add_f32_e32 v16, v16, v19
	v_add_f32_e32 v16, v16, v21
	v_add_f32_e32 v16, v16, v23
	v_add_f32_e32 v16, v16, v25
	v_add_f32_e32 v16, v16, v27
	v_add_f32_e32 v16, v16, v29
	v_add_f32_e32 v16, v16, v31
	v_bfe_u32 v17, v16, 16, 1
	v_add3_u32 v20, v16, v17, s31
	v_lshl_add_u64 v[16:17], s[96:97], 0, v[220:221]
	v_add_co_u32_e32 v18, vcc, s76, v16
	ds_read2st64_b32 v[22:23], v239 offset0:34 offset1:35
	ds_read2st64_b32 v[24:25], v239 offset0:66 offset1:67
	ds_read2st64_b32 v[26:27], v239 offset0:98 offset1:99
	v_addc_co_u32_e32 v19, vcc, 0, v17, vcc
	global_store_short_d16_hi v[18:19], v20, off offset:-4096
	ds_read2st64_b32 v[20:21], v239 offset0:2 offset1:3
	ds_read2st64_b32 v[28:29], v239 offset0:130 offset1:131
	ds_read2st64_b32 v[30:31], v239 offset0:162 offset1:163
	ds_read2st64_b32 v[32:33], v239 offset0:194 offset1:195
	ds_read2st64_b32 v[34:35], v239 offset0:226 offset1:227
	s_waitcnt lgkmcnt(4)
	v_add_f32_e32 v20, 0, v20
	v_add_f32_e32 v20, v20, v22
	v_add_f32_e32 v20, v20, v24
	v_add_f32_e32 v20, v20, v26
	s_waitcnt lgkmcnt(3)
	v_add_f32_e32 v20, v20, v28
	s_waitcnt lgkmcnt(2)
	v_add_f32_e32 v20, v20, v30
	s_waitcnt lgkmcnt(1)
	v_add_f32_e32 v20, v20, v32
	s_waitcnt lgkmcnt(0)
	v_add_f32_e32 v20, v20, v34
	v_bfe_u32 v22, v20, 16, 1
	v_add3_u32 v20, v20, v22, s31
	global_store_short_d16_hi v[18:19], v20, off
	v_add_f32_e32 v18, 0, v21
	v_add_f32_e32 v18, v18, v23
	v_add_f32_e32 v18, v18, v25
	v_add_f32_e32 v18, v18, v27
	v_add_f32_e32 v18, v18, v29
	v_add_f32_e32 v18, v18, v31
	v_add_f32_e32 v18, v18, v33
	v_add_f32_e32 v18, v18, v35
	s_mov_b32 s13, 0x2d403000
	v_bfe_u32 v19, v18, 16, 1
	v_add_co_u32_e32 v16, vcc, s13, v16
	v_add3_u32 v18, v18, v19, s31
	s_nop 0
	v_addc_co_u32_e32 v17, vcc, 0, v17, vcc
	global_store_short_d16_hi v[16:17], v18, off
	v_add_u32_e32 v16, s12, v137
	v_and_b32_sdwa v18, v3, v238 dst_sel:DWORD dst_unused:UNUSED_PAD src0_sel:WORD_1 src1_sel:DWORD
	v_and_b32_sdwa v19, v1, v238 dst_sel:DWORD dst_unused:UNUSED_PAD src0_sel:WORD_1 src1_sel:DWORD
	ds_read_b128 v[124:127], v16
	ds_read_b128 v[120:123], v16 offset:1024
	ds_read_b128 v[116:119], v16 offset:2048
	ds_read_b128 v[112:115], v16 offset:3072
	v_and_b32_sdwa v16, v2, v238 dst_sel:DWORD dst_unused:UNUSED_PAD src0_sel:WORD_1 src1_sel:DWORD
	v_and_b32_sdwa v17, v0, v238 dst_sel:DWORD dst_unused:UNUSED_PAD src0_sel:WORD_1 src1_sel:DWORD
	v_add3_u32 v18, v3, v18, s31
	v_add3_u32 v19, v1, v19, s31
	v_add3_u32 v17, v0, v17, s31
	v_add3_u32 v16, v2, v16, s31
	v_and_b32_e32 v18, 0xffff0000, v18
	v_and_b32_e32 v19, 0xffff0000, v19
	v_or_b32_sdwa v129, v18, v16 dst_sel:DWORD dst_unused:UNUSED_PAD src0_sel:DWORD src1_sel:WORD_1
	v_or_b32_sdwa v128, v19, v17 dst_sel:DWORD dst_unused:UNUSED_PAD src0_sel:DWORD src1_sel:WORD_1
	v_and_b32_sdwa v18, v7, v238 dst_sel:DWORD dst_unused:UNUSED_PAD src0_sel:WORD_1 src1_sel:DWORD
	v_and_b32_sdwa v19, v5, v238 dst_sel:DWORD dst_unused:UNUSED_PAD src0_sel:WORD_1 src1_sel:DWORD
	v_and_b32_sdwa v16, v6, v238 dst_sel:DWORD dst_unused:UNUSED_PAD src0_sel:WORD_1 src1_sel:DWORD
	v_and_b32_sdwa v17, v4, v238 dst_sel:DWORD dst_unused:UNUSED_PAD src0_sel:WORD_1 src1_sel:DWORD
	v_add3_u32 v18, v7, v18, s31
	v_add3_u32 v19, v5, v19, s31
	v_add3_u32 v17, v4, v17, s31
	v_add3_u32 v16, v6, v16, s31
	v_and_b32_e32 v18, 0xffff0000, v18
	v_and_b32_e32 v19, 0xffff0000, v19
	v_or_b32_sdwa v131, v18, v16 dst_sel:DWORD dst_unused:UNUSED_PAD src0_sel:DWORD src1_sel:WORD_1
	v_or_b32_sdwa v130, v19, v17 dst_sel:DWORD dst_unused:UNUSED_PAD src0_sel:DWORD src1_sel:WORD_1
	v_and_b32_sdwa v18, v11, v238 dst_sel:DWORD dst_unused:UNUSED_PAD src0_sel:WORD_1 src1_sel:DWORD
	v_and_b32_sdwa v19, v9, v238 dst_sel:DWORD dst_unused:UNUSED_PAD src0_sel:WORD_1 src1_sel:DWORD
	v_and_b32_sdwa v16, v10, v238 dst_sel:DWORD dst_unused:UNUSED_PAD src0_sel:WORD_1 src1_sel:DWORD
	v_and_b32_sdwa v17, v8, v238 dst_sel:DWORD dst_unused:UNUSED_PAD src0_sel:WORD_1 src1_sel:DWORD
	v_add3_u32 v18, v11, v18, s31
	v_add3_u32 v19, v9, v19, s31
	v_add3_u32 v17, v8, v17, s31
	v_add3_u32 v16, v10, v16, s31
	v_and_b32_e32 v18, 0xffff0000, v18
	v_and_b32_e32 v19, 0xffff0000, v19
	v_or_b32_sdwa v133, v18, v16 dst_sel:DWORD dst_unused:UNUSED_PAD src0_sel:DWORD src1_sel:WORD_1
	v_or_b32_sdwa v132, v19, v17 dst_sel:DWORD dst_unused:UNUSED_PAD src0_sel:DWORD src1_sel:WORD_1
	v_and_b32_sdwa v18, v15, v238 dst_sel:DWORD dst_unused:UNUSED_PAD src0_sel:WORD_1 src1_sel:DWORD
	v_and_b32_sdwa v19, v13, v238 dst_sel:DWORD dst_unused:UNUSED_PAD src0_sel:WORD_1 src1_sel:DWORD
	v_and_b32_sdwa v16, v14, v238 dst_sel:DWORD dst_unused:UNUSED_PAD src0_sel:WORD_1 src1_sel:DWORD
	v_and_b32_sdwa v17, v12, v238 dst_sel:DWORD dst_unused:UNUSED_PAD src0_sel:WORD_1 src1_sel:DWORD
	v_add3_u32 v18, v15, v18, s31
	v_add3_u32 v19, v13, v19, s31
	v_add3_u32 v17, v12, v17, s31
	v_add3_u32 v16, v14, v16, s31
	v_and_b32_e32 v18, 0xffff0000, v18
	v_and_b32_e32 v19, 0xffff0000, v19
	v_or_b32_sdwa v135, v18, v16 dst_sel:DWORD dst_unused:UNUSED_PAD src0_sel:DWORD src1_sel:WORD_1
	v_or_b32_sdwa v134, v19, v17 dst_sel:DWORD dst_unused:UNUSED_PAD src0_sel:DWORD src1_sel:WORD_1
	s_waitcnt vmcnt(16)
	v_mfma_f32_32x32x16_bf16 v[16:31], v[104:107], v[128:131], 0
	s_and_b64 vcc, exec, s[4:5]
	s_waitcnt vmcnt(15)
	v_mfma_f32_32x32x16_bf16 v[16:31], v[108:111], v[132:135], v[16:31]
	s_cbranch_vccnz .LBB0_829
	s_mov_b64 s[12:13], -1
	s_and_b64 vcc, exec, s[44:45]
	s_cbranch_vccz .LBB0_826
	s_mov_b64 s[60:61], -1
	s_mov_b64 s[12:13], 0
	s_cmp_lt_i32 s65, 2
	s_mov_b64 s[58:59], 0
	s_cbranch_scc1 .LBB0_821
	s_cmp_eq_u32 s65, 2
	s_mov_b64 s[58:59], -1
	s_cbranch_scc0 .LBB0_818
	s_mov_b64 s[58:59], 0
	s_waitcnt vmcnt(12) lgkmcnt(1)
	s_nop 2
	v_mfma_f32_32x32x16_bf16 v[16:31], v[56:59], v[116:119], v[16:31]

.LBB0_820:
	s_waitcnt vmcnt(12) lgkmcnt(0)
	s_nop 2
	v_mfma_f32_32x32x16_bf16 v[16:31], v[56:59], v[112:115], v[16:31]
	s_cbranch_execz .LBB0_824
	s_branch .LBB0_825

.LBB0_824:
	s_waitcnt vmcnt(12) lgkmcnt(2)
	s_nop 2
	v_mfma_f32_32x32x16_bf16 v[16:31], v[56:59], v[120:123], v[16:31]

.LBB0_826:
	s_and_b64 vcc, exec, s[12:13]
	s_cbranch_vccz .LBB0_828
	s_waitcnt vmcnt(12) lgkmcnt(3)
	s_nop 2
	v_mfma_f32_32x32x16_bf16 v[16:31], v[56:59], v[124:127], v[16:31]
	s_nop 11
.LBB0_828:
	s_nop 8
.LBB0_829:
	s_nop 10
	ds_write2st64_b32 v237, v16, v17 offset1:1
	ds_write2st64_b32 v237, v18, v19 offset0:2 offset1:3
	ds_write2st64_b32 v237, v20, v21 offset0:4 offset1:5
	ds_write2st64_b32 v237, v22, v23 offset0:6 offset1:7
	ds_write2st64_b32 v237, v24, v25 offset0:8 offset1:9
	ds_write2st64_b32 v237, v26, v27 offset0:10 offset1:11
	ds_write2st64_b32 v237, v28, v29 offset0:12 offset1:13
	ds_write2st64_b32 v237, v30, v31 offset0:14 offset1:15
	s_waitcnt vmcnt(14)
	v_mfma_f32_32x32x16_bf16 v[16:31], v[96:99], v[128:131], 0
	s_and_b64 vcc, exec, s[6:7]
	s_waitcnt vmcnt(13)
	v_mfma_f32_32x32x16_bf16 v[16:31], v[100:103], v[132:135], v[16:31]
	s_cbranch_vccnz .LBB0_845
	s_mov_b64 s[12:13], -1
	s_and_b64 vcc, exec, s[44:45]
	s_cbranch_vccz .LBB0_842
	s_mov_b64 s[60:61], -1
	s_mov_b64 s[12:13], 0
	s_cmp_lt_i32 s65, 2
	s_mov_b64 s[58:59], 0
	s_cbranch_scc1 .LBB0_837
	s_cmp_eq_u32 s65, 2
	s_mov_b64 s[58:59], -1
	s_cbranch_scc0 .LBB0_834
	s_mov_b64 s[58:59], 0
	s_waitcnt vmcnt(12) lgkmcnt(9)
	s_nop 2
	v_mfma_f32_32x32x16_bf16 v[16:31], v[56:59], v[116:119], v[16:31]

.LBB0_836:
	s_waitcnt vmcnt(12) lgkmcnt(8)
	s_nop 2
	v_mfma_f32_32x32x16_bf16 v[16:31], v[56:59], v[112:115], v[16:31]
	s_cbranch_execz .LBB0_840
	s_branch .LBB0_841

.LBB0_840:
	s_waitcnt vmcnt(12) lgkmcnt(10)
	s_nop 2
	v_mfma_f32_32x32x16_bf16 v[16:31], v[56:59], v[120:123], v[16:31]

.LBB0_842:
	s_and_b64 vcc, exec, s[12:13]
	s_cbranch_vccz .LBB0_844
	s_waitcnt vmcnt(12) lgkmcnt(11)
	s_nop 2
	v_mfma_f32_32x32x16_bf16 v[16:31], v[56:59], v[124:127], v[16:31]
	s_nop 11
.LBB0_844:
	s_nop 8
.LBB0_845:
	s_nop 10
	ds_write2st64_b32 v237, v16, v17 offset0:16 offset1:17
	ds_write2st64_b32 v237, v18, v19 offset0:18 offset1:19
	ds_write2st64_b32 v237, v20, v21 offset0:20 offset1:21
	ds_write2st64_b32 v237, v22, v23 offset0:22 offset1:23
	ds_write2st64_b32 v237, v24, v25 offset0:24 offset1:25
	ds_write2st64_b32 v237, v26, v27 offset0:26 offset1:27
	ds_write2st64_b32 v237, v28, v29 offset0:28 offset1:29
	v_cndmask_b32_e64 v16, 0, 1, s[56:57]
	v_cmp_ne_u32_e64 s[12:13], 1, v16
	s_andn2_b64 vcc, exec, s[56:57]
	ds_write2st64_b32 v237, v30, v31 offset0:30 offset1:31
	s_cbranch_vccnz .LBB0_847
	v_add_co_u32_e32 v16, vcc, 0x2f528000, v230
	s_nop 1
	v_addc_co_u32_e32 v17, vcc, 0, v231, vcc
	global_load_dwordx4 v[104:107], v[16:17], off
	global_load_dwordx4 v[108:111], v[16:17], off offset:1024
	v_add_co_u32_e32 v16, vcc, 0x2f52c000, v230
	s_nop 1
	v_addc_co_u32_e32 v17, vcc, 0, v231, vcc
	global_load_dwordx4 v[96:99], v[16:17], off
	global_load_dwordx4 v[100:103], v[16:17], off offset:1024
	v_add_co_u32_e32 v16, vcc, 0x3160a000, v232
	s_nop 1
	v_addc_co_u32_e32 v17, vcc, 0, v233, vcc
	global_load_dwordx4 v[56:59], v[16:17], off
